# seam L1 invalidate issued by wave 1 so thread 0's flag polls are not queued behind it
# speedup vs baseline: 1.0093x; 1.0009x over previous
.LBB0_409:
	s_add_i32 s70, s70, 1
	s_cmp_ge_i32 s70, s71
	s_mov_b64 s[4:5], -1
	s_waitcnt lgkmcnt(0)
	v_readlane_b32 s24, v239, 20
	v_readlane_b32 s25, v239, 19
	s_cbranch_scc1 .LBB0_10
	v_readlane_b32 s6, v240, 12
	v_readlane_b32 s7, v240, 13
	s_and_b64 vcc, exec, s[6:7]
	s_cbranch_vccz .LBB0_464
	s_getreg_b32 s3, hwreg(HW_REG_XCC_ID, 0, 4)
	s_waitcnt vmcnt(0)
	s_waitcnt vmcnt(0)
	s_barrier
	s_movk_i32 s4, 64
	v_cmp_eq_u32_e32 vcc, s4, v210
	s_and_saveexec_b64 s[4:5], vcc
	s_cbranch_execz .Lxb_noinv
	buffer_inv sc1
.Lxb_noinv:
	s_or_b64 exec, exec, s[4:5]
	v_cmp_eq_u32_e32 vcc, 0, v210
	s_and_saveexec_b64 s[4:5], vcc
	s_cbranch_execz .LBB0_463
	v_readlane_b32 s6, v240, 60
	s_and_b32 s3, s3, 15
	s_lshl_b32 s3, s3, 8
	v_mov_b32_e32 v0, s6
	ds_read_b64 v[0:1], v0
	v_readlane_b32 s6, v240, 5
	v_readlane_b32 s7, v240, 6
	s_waitcnt lgkmcnt(0)
	v_cmp_ne_u32_e32 vcc, 0, v0
	s_cbranch_vccnz .Lxb_have
	s_mov_b32 s12, 0

.Lxb_have:
	v_readfirstlane_b32 s10, v0
	v_readfirstlane_b32 s11, v1
	v_readlane_b32 s8, v240, 60
	s_add_i32 s101, s101, 1
	v_mov_b32_e32 v2, 1
	s_nop 1
	v_mov_b32_e32 v4, s8
	ds_read_b32 v4, v4 offset:8
	v_readlane_b32 s8, v240, 0
	s_nop 0
	s_lshl_b32 s9, s8, 6
	s_add_u32 s9, s9, 0x4000
	s_add_u32 s14, s6, s9
	s_addc_u32 s15, s7, 0
	s_waitcnt lgkmcnt(0)
	v_readfirstlane_b32 s9, v4
	s_cmp_eq_u32 s9, 1
	s_cbranch_scc0 .Lxb_grid
	s_mov_b32 s9, 0x3cfdf3f4
	s_bitcmp1_b32 s9, s70
	s_cbranch_scc0 .Lxb_grid
	s_and_b32 s9, s8, 7
	s_lshl_b32 s9, s9, 8
	s_add_u32 s9, s9, 0x12000
	s_add_u32 s12, s6, s9
	s_addc_u32 s13, s7, 0
	s_lshr_b32 s9, s8, 3
	s_lshl_b32 s9, s9, 2
	v_mov_b32_e32 v3, s9
	v_mov_b32_e32 v2, s101
	global_store_dword v3, v2, s[12:13]
	s_mov_b32 s9, 0
	s_mov_b32 exec_lo, -1
	s_mov_b32 exec_hi, 0
	v_mbcnt_lo_u32_b32 v3, -1, 0
	v_lshlrev_b32_e32 v3, 2, v3

.Lxb_grid:
	s_add_i32 s100, s100, 1
	s_mul_i32 s10, s10, s100
	s_mul_i32 s11, s11, s100
	s_add_u32 s12, s6, s3
	s_addc_u32 s13, s7, 0
	global_atomic_add v3, v196, v2, s[12:13] offset:1024 sc0
	s_mov_b32 s9, 0
	s_waitcnt vmcnt(0)
	v_add_u32_e32 v3, 1, v3
	v_cmp_eq_u32_e32 vcc, s10, v3
	s_cbranch_vccz .Lxb_poll
	buffer_wbl2 sc1
	v_readlane_b32 s12, v240, 46
	v_readlane_b32 s13, v240, 47
	s_waitcnt vmcnt(0)
	s_nop 3
	global_atomic_add v3, v165, v2, s[12:13] sc0
	s_waitcnt vmcnt(0)
	v_add_u32_e32 v3, 1, v3
	v_cmp_eq_u32_e32 vcc, s11, v3
	s_cbranch_vccz .Lxb_poll
	s_add_u32 s12, s6, 0x4000
	s_addc_u32 s13, s7, 0
	s_mov_b64 exec, -1
	v_mbcnt_lo_u32_b32 v3, -1, 0
	v_mbcnt_hi_u32_b32 v3, -1, v3
	v_mov_b32_e32 v2, 1
	v_lshlrev_b32_e32 v3, 6, v3
	v_add_u32_e32 v4, 0x1000, v3
	v_add_u32_e32 v5, 0x2000, v3
	v_add_u32_e32 v6, 0x3000, v3
	global_atomic_add v3, v2, s[12:13]
	global_atomic_add v4, v2, s[12:13]
	global_atomic_add v5, v2, s[12:13]
	global_atomic_add v6, v2, s[12:13]
	s_waitcnt vmcnt(4)
	s_mov_b64 exec, 1
	s_branch .LBB0_463

.LBB0_463:
	s_or_b64 exec, exec, s[4:5]
	s_mov_b64 s[4:5], 0
	s_waitcnt vmcnt(0) lgkmcnt(0)
	s_barrier
